# v62 + P2 order remap: odd workgroups of rot 0 (S5 first) run rot 2's order (HGRN2 chunk pass first)
# speedup vs baseline: 1.0048x; 1.0038x over previous
; #define STAMP(i) do { if (F.bid == AMP_BLK && F.tid == 0) { const unsigned long long t_ = __builtin_amdgcn_s_memrealtime(); volatile LAS unsigned* M_ = (volatile LAS unsigned*)(F.lds + LDS_BYTES - 512); M_[64 + 2 * (i)] = (unsigned)t_; M_[65 + 2 * (i)] = (unsigned)(t_ >> 32); } } while (0)
; #define STAMP(i) do { } while (0)
; __global__ void __launch_bounds__(NWAVES * 64, 2) mk_fwd(Args args) {
;     ...
;         const int nper = (1024 + F.G - 1) / F.G, rot = F.bid % 3;
;         STAMP(30);
;         if (rot == 0) {
;             STAMP(4);
;             for (int it = F.bid; it < 256; it += F.G) s5_item(F, it);
;             STAMP(5);
;             hgA_loop(F, 0, nper);
;             STAMP(6);
;             hgrn_sample_loop(F);
;             STAMP(7);
;         } else if (rot == 1) {
;             hgrn_sample_loop(F);
;             hgA_loop(F, 0, nper);
;             __syncthreads();
;             for (int it = F.bid; it < 256; it += F.G) s5_item(F, it);
;         } else {
;             hgA_loop(F, 0, nper);
;             __syncthreads();
;             for (int it = F.bid; it < 256; it += F.G) s5_item(F, it);
;             hgrn_sample_loop(F);
;         }
.LBB0_274:
	v_readlane_b32 s0, v238, 0
	v_readlane_b32 s1, v238, 1
	s_cmp_lt_i32 s0, 3
	s_cselect_b64 s[0:1], -1, 0
	s_add_u32 s6, s50, 0xa300000
	s_addc_u32 s7, s51, 0
	v_writelane_b32 v238, s6, 47
	s_and_b64 s[0:1], s[0:1], s[4:5]
	s_nop 0
	v_writelane_b32 v238, s7, 48
	v_writelane_b32 v238, s0, 49
	s_andn2_b64 vcc, exec, s[0:1]
	s_nop 0
	v_writelane_b32 v238, s1, 50
	s_cbranch_vccnz .LBB0_551
	s_abs_i32 s0, s52
	v_cvt_f32_u32_e32 v2, s0
	s_sub_i32 s4, 0, s0
	s_add_i32 s3, s52, 0x3ff
	s_ashr_i32 s1, s3, 31
	v_rcp_iflag_f32_e32 v2, v2
	s_abs_i32 s3, s3
	s_ashr_i32 s53, s52, 31
	s_xor_b32 s1, s1, s53
	v_mul_f32_e32 v2, 0x4f7ffffe, v2
	v_cvt_u32_f32_e32 v2, v2
	s_nop 0
	v_readfirstlane_b32 s5, v2
	s_mul_i32 s4, s4, s5
	s_mul_hi_u32 s4, s5, s4
	s_add_i32 s5, s5, s4
	s_mul_hi_u32 s4, s3, s5
	s_mul_i32 s5, s4, s0
	s_sub_i32 s3, s3, s5
	s_add_i32 s5, s4, 1
	s_sub_i32 s6, s3, s0
	s_cmp_ge_u32 s3, s0
	s_cselect_b32 s4, s5, s4
	s_cselect_b32 s3, s6, s3
	s_add_i32 s5, s4, 1
	s_cmp_ge_u32 s3, s0
	s_cselect_b32 s0, s5, s4
	s_xor_b32 s0, s0, s1
	s_sub_i32 s0, s0, s1
	v_writelane_b32 v238, s0, 51
	s_mul_hi_i32 s0, s2, 0x55555556
	s_lshr_b32 s1, s0, 31
	s_add_i32 s0, s0, s1
	s_mul_i32 s0, s0, 3
	s_sub_i32 s0, s2, s0
	s_and_b32 s1, s2, 1
	s_lshl_b32 s1, s1, 1
	s_cmp_eq_u32 s0, 0
	s_cselect_b32 s0, s1, s0
	s_mov_b64 s[4:5], -1
	v_writelane_b32 v238, s0, 52
	s_cmp_lt_i32 s0, 1
	s_mov_b64 s[0:1], 0
	v_writelane_b32 v238, s96, 53
	s_cbranch_scc1 .LBB0_290
	v_readlane_b32 s0, v238, 52
	s_cmp_eq_u32 s0, 1
	s_mov_b64 s[0:1], -1
	s_cbranch_scc0 .LBB0_372
	s_cmpk_lt_i32 s2, 0x200
	s_cbranch_scc0 .LBB0_293
; #define GAS __attribute__((address_space(1)))
; #define LAS __attribute__((address_space(3)))
; __device__ __forceinline__ void hgrn_sample_loop(Frame& F) {
;     const int tid = F.tid;
;     LAS float* Qs = (LAS float*)(F.lds + LX_Q); LAS float* K2 = (LAS float*)(F.lds + LX_K2); LAS float* QT = (LAS float*)(F.lds + LX_QT); LAS float* K3T = (LAS float*)(F.lds + LX_K3T); LAS float* Vs = (LAS float*)(F.lds + LX_V);
;     LAS float* DEC = (LAS float*)(F.lds + LX_DEC); LAS float* ATT = (LAS float*)(F.lds + LX_ATT); LAS float* OP = (LAS float*)(F.lds + LX_OP); LAS float* OT = (LAS float*)(F.lds + LX_OT);
;     const bf16* PB = (const bf16*)(F.ws + WS_PB); const float* FZ = (const float*)(F.ws + WS_FZ); bf16* MIX = (bf16*)(F.ws + WS_MIX);
;     const int v4 = (tid & 31) * 4, kg = tid >> 5;
;     int idx = F.bid; if (idx >= SB_B * HH) return;
;     f32x4 s0[8];
; #pragma unroll
;     for (int j = 0; j < 8; ++j) s0[j] = *(const GAS f32x4*)(F.in[4] + (size_t)idx * HD * HD + (size_t)(8 * kg + j) * HD + v4);
	s_ashr_i32 s3, s2, 31
	v_readlane_b32 s60, v238, 4
	v_lshrrev_b32_e32 v36, 5, v0
	s_lshl_b64 s[4:5], s[2:3], 16
	v_readlane_b32 s68, v238, 12
	v_lshlrev_b32_e32 v4, 3, v36
	v_mov_b32_e32 v135, 0
	v_readlane_b32 s69, v238, 13
	s_add_u32 s0, s68, s4
	v_lshlrev_b32_e32 v6, 4, v0
	v_or_b32_e32 v37, 1, v4
	v_or_b32_e32 v38, 2, v4
	v_or_b32_e32 v39, 3, v4
	v_or_b32_e32 v40, 4, v4
	v_or_b32_e32 v41, 5, v4
	v_or_b32_e32 v42, 6, v4
	v_or_b32_e32 v43, 7, v4
	s_addc_u32 s1, s69, s5
	v_and_b32_e32 v34, 0x1f0, v6
	v_mov_b32_e32 v35, v135
	v_lshlrev_b32_e32 v132, 12, v36
	v_mov_b32_e32 v133, v135
	v_lshlrev_b32_e32 v134, 9, v37
	v_lshlrev_b32_e32 v18, 9, v38
	v_mov_b32_e32 v19, v135
	v_lshlrev_b32_e32 v20, 9, v39
	v_mov_b32_e32 v21, v135
	v_lshlrev_b32_e32 v10, 9, v40
	v_mov_b32_e32 v11, v135
	v_lshlrev_b32_e32 v12, 9, v41
	v_mov_b32_e32 v13, v135
	v_lshlrev_b32_e32 v2, 9, v42
	v_mov_b32_e32 v3, v135
	v_lshlrev_b32_e32 v4, 9, v43
	v_mov_b32_e32 v5, v135
	v_lshl_add_u64 v[26:27], s[0:1], 0, v[34:35]
	v_lshl_add_u64 v[4:5], v[26:27], 0, v[4:5]
	v_lshl_add_u64 v[6:7], v[26:27], 0, v[2:3]
	v_lshl_add_u64 v[12:13], v[26:27], 0, v[12:13]
	v_lshl_add_u64 v[14:15], v[26:27], 0, v[10:11]
	v_lshl_add_u64 v[20:21], v[26:27], 0, v[20:21]
	v_lshl_add_u64 v[22:23], v[26:27], 0, v[18:19]
	v_lshl_add_u64 v[28:29], v[26:27], 0, v[134:135]
	v_lshl_add_u64 v[30:31], v[26:27], 0, v[132:133]
	global_load_dwordx4 v[2:5], v[4:5], off nt
	s_nop 0
	global_load_dwordx4 v[6:9], v[6:7], off nt
	s_nop 0
	global_load_dwordx4 v[10:13], v[12:13], off nt
	s_nop 0
	global_load_dwordx4 v[14:17], v[14:15], off nt
	s_nop 0
	global_load_dwordx4 v[18:21], v[20:21], off nt
	s_nop 0
	global_load_dwordx4 v[22:25], v[22:23], off nt
	s_nop 0
	global_load_dwordx4 v[26:29], v[28:29], off nt
	s_nop 0
	global_load_dwordx4 v[30:33], v[30:31], off nt
	v_and_b32_e32 v44, 7, v0
	v_lshrrev_b32_e32 v45, 6, v0
	v_bfe_u32 v46, v0, 3, 3
	v_lshlrev_b32_e32 v47, 9, v45
	v_lshlrev_b32_e32 v48, 2, v44
	v_add3_u32 v148, 0, v47, v48
	v_lshlrev_b32_e32 v47, 9, v46
	v_add3_u32 v149, 0, v47, v48
	v_mbcnt_lo_u32_b32 v47, -1, 0
	v_mbcnt_hi_u32_b32 v47, -1, v47
	s_movk_i32 s0, 0x80
	v_and_b32_e32 v49, 64, v47
	v_subrev_co_u32_e32 v134, vcc, s0, v0
	v_xor_b32_e32 v48, 1, v47
	v_add_u32_e32 v49, 64, v49
	s_xor_b64 s[10:11], vcc, -1
	v_cmp_lt_i32_e32 vcc, v48, v49
	v_add_u32_e32 v131, 0, v34
	v_lshrrev_b32_e32 v34, 3, v0
	v_cndmask_b32_e32 v48, v47, v48, vcc
	v_lshlrev_b32_e32 v150, 2, v48
	v_xor_b32_e32 v48, 2, v47
	v_cmp_lt_i32_e32 vcc, v48, v49
	v_lshl_add_u32 v153, v34, 2, 0
	v_and_b32_e32 v130, 0x7f, v0
	v_cndmask_b32_e32 v48, v47, v48, vcc
	v_lshlrev_b32_e32 v151, 2, v48
	v_xor_b32_e32 v48, 4, v47
	v_cmp_lt_i32_e32 vcc, v48, v49
	v_xor_b32_e32 v34, 8, v47
	v_cmp_eq_u32_e64 s[6:7], 0, v44
	v_cndmask_b32_e32 v48, v47, v48, vcc
	v_lshl_add_u32 v155, v130, 2, 0
	v_cmp_lt_i32_e32 vcc, v34, v49
	v_lshl_add_u32 v159, v36, 8, 0
	v_mul_i32_i24_e32 v44, 0xffffff20, v36
	v_and_b32_e32 v36, 0x180, v0
	v_cndmask_b32_e32 v34, v47, v34, vcc
	v_lshl_add_u32 v167, v36, 2, v155
	v_lshrrev_b32_e32 v36, 2, v0
	v_readlane_b32 s12, v238, 29
	v_lshlrev_b32_e32 v156, 2, v34
	v_xor_b32_e32 v34, 16, v47
	v_lshl_add_u32 v161, v38, 5, 0
	v_and_b32_e32 v38, 0x60, v36
	s_movk_i32 s3, 0x380
	v_mov_b32_e32 v36, 0x200
	v_readlane_b32 s13, v238, 30
	s_add_i32 s12, s2, s52
	v_cmp_lt_i32_e32 vcc, v34, v49
	v_bitop3_b32 v36, v0, s3, v36 bitop3:0xc8
	s_lshl_b32 s3, s96, 9
	s_ashr_i32 s13, s12, 31
	v_cndmask_b32_e32 v34, v47, v34, vcc
	s_add_i32 s3, s3, 0
	s_lshl_b64 s[12:13], s[12:13], 16
	v_lshlrev_b32_e32 v157, 2, v34
	v_xor_b32_e32 v34, 32, v47
	s_add_u32 s12, s68, s12
	v_cmp_lt_i32_e32 vcc, v34, v49
	v_lshl_add_u32 v169, v36, 2, v155
	v_lshlrev_b32_e32 v36, 3, v154
	s_addc_u32 s13, s69, s13
	v_cndmask_b32_e32 v34, v47, v34, vcc
	v_add_u32_e32 v171, s3, v36
	v_lshl_add_u64 v[140:141], s[12:13], 0, v[132:133]
	s_lshl_b64 s[12:13], s[52:53], 16
	s_lshl_b32 s3, s2, 1
	s_lshl_b32 s33, s52, 1
	v_lshlrev_b32_e32 v158, 2, v34
	v_or_b32_e32 v34, 0x200, v0
	v_lshl_add_u32 v160, v37, 5, 0
	v_mov_b32_e32 v37, v135
	v_readlane_b32 s14, v238, 31
	v_readlane_b32 s15, v238, 32
	s_add_u32 s4, s48, s4
	v_lshl_add_u32 v146, v0, 2, 0
	v_lshrrev_b32_e32 v34, 2, v34
	v_lshl_add_u64 v[136:137], s[14:15], 0, v[36:37]
	v_and_b32_e32 v36, 31, v0
	s_addc_u32 s5, s49, s5
	s_movk_i32 s0, 0x100
	v_mad_u32_u24 v147, v0, 28, v146
	v_mul_i32_i24_e32 v35, 0xffffffe4, v0
	v_lshl_add_u32 v162, v39, 5, 0
	v_and_b32_e32 v39, 0xe0, v34
	v_lshlrev_b32_e32 v34, 1, v154
	v_lshlrev_b32_e32 v138, 4, v36
	v_lshl_add_u64 v[36:37], s[4:5], 0, v[132:133]
	s_mov_b64 s[4:5], 0x4820800
	v_cmp_gt_u32_e64 s[0:1], s0, v0
	v_lshlrev_b32_e32 v152, 2, v48
	v_cmp_gt_u32_e64 s[8:9], v46, v45
	v_lshl_add_u32 v163, v40, 5, 0
	v_lshl_add_u32 v164, v41, 5, 0
	v_lshl_add_u32 v165, v42, 5, 0
	v_lshl_add_u32 v166, v43, 5, 0
	v_add_u32_e32 v168, 0x6300, v167
	v_add_u32_e32 v170, 0x6300, v169
	v_mov_b32_e32 v139, v135
	v_lshl_add_u64 v[142:143], v[36:37], 0, s[4:5]
	v_lshlrev_b64 v[144:145], 1, v[134:135]
	v_add_u32_e32 v133, v147, v35
	v_add_u32_e32 v172, v159, v44
	v_add_u32_e32 v173, 0, v38
	v_add_u32_e32 v174, 0, v39
	v_lshlrev_b32_e32 v134, 1, v34
	v_mov_b32_e32 v175, 0x358637bd
	s_mov_b32 s34, s2
	v_readlane_b32 s61, v238, 5
	v_readlane_b32 s62, v238, 6
	v_readlane_b32 s63, v238, 7
	v_readlane_b32 s64, v238, 8
	v_readlane_b32 s65, v238, 9
	v_readlane_b32 s66, v238, 10
	v_readlane_b32 s67, v238, 11
	v_readlane_b32 s70, v238, 14
	v_readlane_b32 s71, v238, 15
	v_readlane_b32 s72, v238, 16
	v_readlane_b32 s73, v238, 17
	v_readlane_b32 s74, v238, 18
	v_readlane_b32 s75, v238, 19
	v_readlane_b32 s16, v238, 33
	v_readlane_b32 s17, v238, 34
	v_readlane_b32 s18, v238, 35
	v_readlane_b32 s19, v238, 36
	v_readlane_b32 s20, v238, 37
	v_readlane_b32 s21, v238, 38
	v_readlane_b32 s22, v238, 39
	v_readlane_b32 s23, v238, 40
	v_readlane_b32 s24, v238, 41
	v_readlane_b32 s25, v238, 42
	v_readlane_b32 s26, v238, 43
	v_readlane_b32 s27, v238, 44
	s_branch .LBB0_280
